# same shared barrier routine with the baseline's spin bound (2^18 polls) instead of 2^14
# speedup vs baseline: 1.0006x; 1.0001x over previous
.Lmb_spin_top:
	global_load_dword v252, v250, s[100:101] sc1
	s_waitcnt vmcnt(0)
	v_cmp_lt_u32_e32 vcc, v252, v253
	s_cbranch_vccz .Lmb_top_ok
	s_sleep 1
	v_add_u32_e32 v255, 1, v255
	v_cmp_gt_u32_e32 vcc, 0x40000, v255
	s_cbranch_vccnz .Lmb_spin_top

.Lmb_spin_loc:
	global_load_dword v252, v254, s[100:101] sc1
	s_waitcnt vmcnt(0)
	v_cmp_lt_u32_e32 vcc, v252, v253
	s_cbranch_vccz .Lmb_loc_ok
	s_sleep 1
	v_add_u32_e32 v255, 1, v255
	v_cmp_gt_u32_e32 vcc, 0x40000, v255
	s_cbranch_vccnz .Lmb_spin_loc
